# v47 + scan3 sample tail and attn_combine rewritten with all loads of an item in flight together
# speedup vs baseline: 1.0129x; 1.0129x over previous
; __device__ __forceinline__ bf16 f2bf1(float f) { return (bf16)(cvt_pk_bf16(f, 0.f) & 0xffffu); }
; __device__ __forceinline__ float bf2f(bf16 b) { return __uint_as_float((unsigned)b << 16); }
; __device__ __forceinline__ float fsqrt(float x) { return __builtin_amdgcn_sqrtf(x); }
; __device__ __forceinline__ void scan_pass3(const Frame& F, CArgs* A, int j, const bf16* OMA, const bf16* GI, const float* HIN, const bf16* GG, bf16* HG) {
;     ...
;     for (int i = F.gt; i < SB * 2048; i += F.ngt) { const int b = i >> 11, col = i & 2047; float h = A->in[I_SLH][(size_t)(j * SB + b) * 2048 + col];
; #pragma unroll
;         for (int t = 0; t < ST; ++t) { const size_t k = (size_t)(MP + b * ST + t) * 2048 + col; const float o = bf2f(OMA[k]), a = 1.f - o; h = a * h + fsqrt(o * (1.f + a)) * bf2f(GI[k]); HG[k] = f2bf1(h * bf2f(GG[k])); }
;         A->out[O_LHS + (size_t)(j * SB + b) * 2048 + col] = h; }
.LBB0_586:
	s_load_dwordx2 s[26:27], s[0:1], 0x28
	s_load_dwordx2 s[34:35], s[0:1], 0xe0
	v_ashrrev_i32_e32 v7, 11, v6
	v_add_u32_e32 v2, s15, v7
	v_ashrrev_i32_e32 v3, 31, v2
	v_and_b32_e32 v8, 0x7ff, v6
	v_lshlrev_b64 v[2:3], 13, v[2:3]
	v_lshlrev_b32_e32 v0, 2, v8
	v_lshlrev_b32_e32 v4, 2, v7
	v_ashrrev_i32_e32 v5, 31, v4
	v_lshlrev_b64 v[4:5], 12, v[4:5]
	v_lshl_or_b32 v4, v8, 1, v4
	s_mov_b64 s[38:39], 0x2001000
	s_mov_b64 s[40:41], 0x2002000
	s_mov_b64 s[42:43], 0x2003000
	v_lshl_add_u64 v[20:21], v[4:5], 0, s[28:29]
	v_lshl_add_u64 v[22:23], v[4:5], 0, s[38:39]
	v_lshl_add_u64 v[24:25], v[4:5], 0, s[40:41]
	v_lshl_add_u64 v[26:27], v[4:5], 0, s[42:43]
	s_waitcnt lgkmcnt(0)
	v_lshl_add_u64 v[28:29], s[26:27], 0, v[2:3]
	v_lshl_add_u64 v[28:29], v[28:29], 0, v[0:1]
	global_load_dword v52, v[28:29], off
	v_lshl_add_u64 v[30:31], s[16:17], 0, v[20:21]
	global_load_ushort v40, v[30:31], off
	v_lshl_add_u64 v[32:33], s[18:19], 0, v[20:21]
	global_load_ushort v41, v[32:33], off
	v_lshl_add_u64 v[30:31], s[2:3], 0, v[20:21]
	global_load_ushort v42, v[30:31], off
	v_lshl_add_u64 v[32:33], s[16:17], 0, v[22:23]
	global_load_ushort v43, v[32:33], off
	v_lshl_add_u64 v[30:31], s[18:19], 0, v[22:23]
	global_load_ushort v44, v[30:31], off
	v_lshl_add_u64 v[32:33], s[2:3], 0, v[22:23]
	global_load_ushort v45, v[32:33], off
	v_lshl_add_u64 v[30:31], s[16:17], 0, v[24:25]
	global_load_ushort v46, v[30:31], off
	v_lshl_add_u64 v[32:33], s[18:19], 0, v[24:25]
	global_load_ushort v47, v[32:33], off
	v_lshl_add_u64 v[30:31], s[2:3], 0, v[24:25]
	global_load_ushort v48, v[30:31], off
	v_lshl_add_u64 v[32:33], s[16:17], 0, v[26:27]
	global_load_ushort v49, v[32:33], off
	v_lshl_add_u64 v[30:31], s[18:19], 0, v[26:27]
	global_load_ushort v50, v[30:31], off
	v_lshl_add_u64 v[32:33], s[2:3], 0, v[26:27]
	global_load_ushort v51, v[32:33], off
	v_add_u32_e32 v6, s14, v6
	s_movk_i32 s20, 0x3fff
	s_waitcnt vmcnt(11)
	v_lshlrev_b32_e32 v40, 16, v40
	v_sub_f32_e32 v10, 1.0, v40
	v_add_f32_e32 v11, 1.0, v10
	v_mul_f32_e32 v40, v11, v40
	v_sqrt_f32_e32 v40, v40
	s_waitcnt vmcnt(10)
	v_lshlrev_b32_e32 v41, 16, v41
	v_mul_f32_e32 v40, v40, v41
	v_fmac_f32_e32 v40, v52, v10
	s_waitcnt vmcnt(9)
	v_lshlrev_b32_e32 v42, 16, v42
	v_mul_f32_e32 v42, v40, v42
	v_cvt_pk_bf16_f32 v42, v42, v1
	v_lshl_add_u64 v[12:13], s[24:25], 0, v[20:21]
	global_store_short v[12:13], v42, off
	s_waitcnt vmcnt(9)
	v_lshlrev_b32_e32 v43, 16, v43
	v_sub_f32_e32 v10, 1.0, v43
	v_add_f32_e32 v11, 1.0, v10
	v_mul_f32_e32 v43, v11, v43
	v_sqrt_f32_e32 v43, v43
	s_waitcnt vmcnt(8)
	v_lshlrev_b32_e32 v44, 16, v44
	v_mul_f32_e32 v43, v43, v44
	v_fmac_f32_e32 v43, v40, v10
	s_waitcnt vmcnt(7)
	v_lshlrev_b32_e32 v45, 16, v45
	v_mul_f32_e32 v45, v43, v45
	v_cvt_pk_bf16_f32 v45, v45, v1
	v_lshl_add_u64 v[12:13], s[24:25], 0, v[22:23]
	global_store_short v[12:13], v45, off
	s_waitcnt vmcnt(7)
	v_lshlrev_b32_e32 v46, 16, v46
	v_sub_f32_e32 v10, 1.0, v46
	v_add_f32_e32 v11, 1.0, v10
	v_mul_f32_e32 v46, v11, v46
	v_sqrt_f32_e32 v46, v46
	s_waitcnt vmcnt(6)
	v_lshlrev_b32_e32 v47, 16, v47
	v_mul_f32_e32 v46, v46, v47
	v_fmac_f32_e32 v46, v43, v10
	s_waitcnt vmcnt(5)
	v_lshlrev_b32_e32 v48, 16, v48
	v_mul_f32_e32 v48, v46, v48
	v_cvt_pk_bf16_f32 v48, v48, v1
	v_lshl_add_u64 v[12:13], s[24:25], 0, v[24:25]
	global_store_short v[12:13], v48, off
	s_waitcnt vmcnt(5)
	v_lshlrev_b32_e32 v49, 16, v49
	v_sub_f32_e32 v10, 1.0, v49
	v_add_f32_e32 v11, 1.0, v10
	v_mul_f32_e32 v49, v11, v49
	v_sqrt_f32_e32 v49, v49
	s_waitcnt vmcnt(4)
	v_lshlrev_b32_e32 v50, 16, v50
	v_mul_f32_e32 v49, v49, v50
	v_fmac_f32_e32 v49, v46, v10
	s_waitcnt vmcnt(3)
	v_lshlrev_b32_e32 v51, 16, v51
	v_mul_f32_e32 v51, v49, v51
	v_cvt_pk_bf16_f32 v51, v51, v1
	v_lshl_add_u64 v[12:13], s[24:25], 0, v[26:27]
	global_store_short v[12:13], v51, off
	v_lshl_add_u64 v[2:3], s[34:35], 0, v[2:3]
	v_lshl_add_u64 v[2:3], v[2:3], 0, v[0:1]
	v_add_co_u32_e32 v2, vcc, 0x96a0000, v2
	s_nop 1
	v_addc_co_u32_e32 v3, vcc, 0, v3, vcc
	v_cmp_lt_i32_e32 vcc, s20, v6
	s_or_b64 s[12:13], vcc, s[12:13]
	global_store_dword v[2:3], v49, off
	s_andn2_b64 exec, exec, s[12:13]
	s_cbranch_execnz .LBB0_586

; __device__ __forceinline__ void unpack8(const v4u w, float (&f)[8]) { f[0] = bf_lo(w.x); f[1] = bf_hi(w.x); f[2] = bf_lo(w.y); f[3] = bf_hi(w.y); f[4] = bf_lo(w.z); f[5] = bf_hi(w.z); f[6] = bf_lo(w.w); f[7] = bf_hi(w.w); }
; __device__ __forceinline__ v4u pack8(const float (&f)[8]) { v4u w; w.x = cvt_pk_bf16(f[0], f[1]); w.y = cvt_pk_bf16(f[2], f[3]); w.z = cvt_pk_bf16(f[4], f[5]); w.w = cvt_pk_bf16(f[6], f[7]); return w; }
; __device__ __forceinline__ void attn_combine(const Frame& F, const bf16* OG, const float* LSE, bf16* O) {
; #pragma unroll 4
;     for (int idx = F.gt; idx < MT * 128; idx += F.ngt) {
;         const int m = idx >> 7, hc = idx & 127, h = hc >> 4;
;         const float l0 = LSE[((size_t)0 * MT + m) * 8 + h], l1 = LSE[((size_t)1 * MT + m) * 8 + h], l2 = LSE[((size_t)2 * MT + m) * 8 + h];
;         const float mx = fmaxf(fmaxf(l0, l1), l2); float w0 = __expf(l0 - mx), w1 = __expf(l1 - mx), w2 = __expf(l2 - mx); const float inv = 1.0f / (w0 + w1 + w2); w0 *= inv; w1 *= inv; w2 *= inv;
;         float a[8], bb[8], cc[8], o[8];
;         unpack8(*(const v4u*)(OG + ((size_t)0 * MT + m) * AW + hc * 8), a); unpack8(*(const v4u*)(OG + ((size_t)1 * MT + m) * AW + hc * 8), bb); unpack8(*(const v4u*)(OG + ((size_t)2 * MT + m) * AW + hc * 8), cc);
; #pragma unroll
;         for (int e = 0; e < 8; ++e) o[e] = w0 * a[e] + w1 * bb[e] + w2 * cc[e];
;         *(v4u*)(O + (size_t)m * AW + hc * 8) = pack8(o);
;     }
.LBB0_1279:
	v_ashrrev_i32_e32 v4, 7, v2
	v_ashrrev_i32_e32 v5, 31, v4
	v_lshrrev_b32_e32 v0, 2, v2
	v_and_b32_e32 v0, 28, v0
	s_mov_b64 s[18:19], 0x2020
	v_lshl_add_u64 v[8:9], v[4:5], 0, s[18:19]
	s_mov_b64 s[18:19], 0x4040
	v_lshl_add_u64 v[12:13], v[4:5], 0, s[18:19]
	v_lshlrev_b64 v[6:7], 5, v[4:5]
	v_lshl_add_u64 v[6:7], s[10:11], 0, v[6:7]
	v_lshl_add_u64 v[6:7], v[6:7], 0, v[0:1]
	global_load_dword v10, v[6:7], off
	v_lshlrev_b64 v[6:7], 5, v[8:9]
	v_lshl_add_u64 v[6:7], s[10:11], 0, v[6:7]
	v_lshl_add_u64 v[6:7], v[6:7], 0, v[0:1]
	global_load_dword v11, v[6:7], off
	v_lshlrev_b64 v[6:7], 5, v[12:13]
	v_lshl_add_u64 v[6:7], s[10:11], 0, v[6:7]
	v_lshl_add_u64 v[6:7], v[6:7], 0, v[0:1]
	global_load_dword v32, v[6:7], off
	v_and_b32_e32 v3, 0x7f, v2
	v_lshlrev_b32_e32 v0, 4, v3
	v_lshlrev_b64 v[18:19], 11, v[4:5]
	v_lshl_add_u64 v[6:7], s[2:3], 0, v[18:19]
	v_lshl_add_u64 v[6:7], v[6:7], 0, v[0:1]
	global_load_dwordx4 v[36:39], v[6:7], off
	v_lshlrev_b64 v[6:7], 11, v[8:9]
	v_lshl_add_u64 v[6:7], s[2:3], 0, v[6:7]
	v_lshl_add_u64 v[6:7], v[6:7], 0, v[0:1]
	global_load_dwordx4 v[28:31], v[6:7], off
	v_lshlrev_b64 v[6:7], 11, v[12:13]
	v_lshl_add_u64 v[6:7], s[2:3], 0, v[6:7]
	v_lshl_add_u64 v[6:7], v[6:7], 0, v[0:1]
	global_load_dwordx4 v[40:43], v[6:7], off
	v_add_u32_e32 v2, s16, v2
	s_mov_b32 s17, 0x100fff
	s_waitcnt vmcnt(3)
	v_max3_f32 v6, v10, v11, v32
	v_sub_f32_e32 v7, v10, v6
	v_mul_f32_e32 v7, 0x3fb8aa3b, v7
	v_exp_f32_e32 v15, v7
	v_sub_f32_e32 v7, v11, v6
	v_mul_f32_e32 v7, 0x3fb8aa3b, v7
	v_sub_f32_e32 v0, v32, v6
	v_exp_f32_e32 v7, v7
	v_mul_f32_e32 v0, 0x3fb8aa3b, v0
	v_exp_f32_e32 v14, v0
	v_add_f32_e32 v0, v15, v7
	v_add_f32_e32 v0, v14, v0
	v_div_scale_f32 v6, s[18:19], v0, v0, 1.0
	v_rcp_f32_e32 v10, v6
	s_nop 0
	v_fma_f32 v11, -v6, v10, 1.0
	v_fmac_f32_e32 v10, v11, v10
	v_div_scale_f32 v11, vcc, 1.0, v0, 1.0
	v_mul_f32_e32 v16, v11, v10
	v_fma_f32 v17, -v6, v16, v11
	v_fmac_f32_e32 v16, v17, v10
	v_fma_f32 v6, -v6, v16, v11
	v_div_fmas_f32 v6, v6, v10, v16
	v_div_fixup_f32 v16, v6, v0, 1.0
	v_lshlrev_b32_e32 v0, 4, v3
	v_mul_f32_e32 v20, v7, v16
	v_cmp_lt_i32_e32 vcc, s17, v2
	s_or_b64 s[14:15], vcc, s[14:15]
	s_waitcnt vmcnt(0)
	v_lshlrev_b32_e32 v3, 16, v28
	v_and_b32_e32 v21, 0xffff0000, v28
	v_lshlrev_b32_e32 v22, 16, v29
	v_and_b32_e32 v23, 0xffff0000, v29
	v_lshlrev_b32_e32 v24, 16, v30
	v_and_b32_e32 v25, 0xffff0000, v30
	v_lshlrev_b32_e32 v26, 16, v31
	v_and_b32_e32 v27, 0xffff0000, v31
	v_pk_mul_f32 v[12:13], v[14:15], v[16:17] op_sel_hi:[1,0]
	v_lshlrev_b32_e32 v17, 16, v36
	v_lshlrev_b32_e32 v15, 16, v39
	v_lshlrev_b32_e32 v16, 16, v40
	v_pk_mul_f32 v[16:17], v[12:13], v[16:17]
	v_lshlrev_b32_e32 v14, 16, v43
	v_fma_f32 v3, v20, v3, v17
	v_add_f32_e32 v3, v16, v3
	v_and_b32_e32 v17, 0xffff0000, v36
	v_and_b32_e32 v16, 0xffff0000, v40
	v_pk_mul_f32 v[16:17], v[12:13], v[16:17]
	s_nop 0
	v_fma_f32 v4, v20, v21, v17
	v_add_f32_e32 v8, v16, v4
	v_lshlrev_b32_e32 v17, 16, v37
	v_lshlrev_b32_e32 v16, 16, v41
	v_pk_mul_f32 v[16:17], v[12:13], v[16:17]
	v_and_b32_e32 v5, 0xffff0000, v37
	v_fma_f32 v4, v20, v22, v17
	v_add_f32_e32 v16, v16, v4
	v_and_b32_e32 v4, 0xffff0000, v41
	v_pk_mul_f32 v[4:5], v[12:13], v[4:5]
	s_nop 0
	v_fma_f32 v5, v20, v23, v5
	v_add_f32_e32 v9, v4, v5
	v_lshlrev_b32_e32 v5, 16, v38
	v_lshlrev_b32_e32 v4, 16, v42
	v_pk_mul_f32 v[4:5], v[12:13], v[4:5]
	s_nop 0
	v_fma_f32 v5, v20, v24, v5
	v_add_f32_e32 v17, v4, v5
	v_and_b32_e32 v5, 0xffff0000, v38
	v_and_b32_e32 v4, 0xffff0000, v42
	v_pk_mul_f32 v[4:5], v[12:13], v[4:5]
	s_nop 0
	v_fma_f32 v5, v20, v25, v5
	v_add_f32_e32 v6, v4, v5
	v_pk_mul_f32 v[4:5], v[12:13], v[14:15]
	s_nop 0
	v_fma_f32 v5, v20, v26, v5
	v_add_f32_e32 v10, v4, v5
	v_and_b32_e32 v5, 0xffff0000, v39
	v_and_b32_e32 v4, 0xffff0000, v43
	v_pk_mul_f32 v[4:5], v[12:13], v[4:5]
	s_nop 0
	v_fma_f32 v5, v20, v27, v5
	v_add_f32_e32 v7, v4, v5
	v_cvt_pk_bf16_f32 v4, v3, v8
	v_cvt_pk_bf16_f32 v5, v16, v9
	v_lshl_add_u64 v[8:9], s[12:13], 0, v[18:19]
	v_lshl_add_u64 v[8:9], v[8:9], 0, v[0:1]
	v_cvt_pk_bf16_f32 v6, v17, v6
	v_cvt_pk_bf16_f32 v7, v10, v7
	global_store_dwordx4 v[8:9], v[4:7], off
	s_andn2_b64 exec, exec, s[14:15]
	s_cbranch_execnz .LBB0_1279
